# outproj epilogue: 16 residual loads in flight per half, gate vector loaded once; attention epilogue gate loads issued together; new pipelined GQA attention loop
# speedup vs baseline: 1.0275x; 1.0237x over previous
; DI float silu(float x) { return x / (1.f + __expf(-x)); }
; DI f32x4 unpack4(u32x2 v) { f32x4 r = {bflo(v.x), bfhi(v.x), bflo(v.y), bfhi(v.y)}; return r; }
; DI u32x2 pack4(f32x4 v) { u32x2 r = {cvtpk(v[0], v[1]), cvtpk(v[2], v[3])}; return r; }
; template <int DQK, bool STATIC>
; DI void attn_item8(const bf16_t* __restrict__ Q, const bf16_t* __restrict__ Kp, const bf16_t* __restrict__ Vt, int nkeys, char* lds,
;                   const bf16_t* __restrict__ Pg, bf16_t* __restrict__ Yg  , float mfix) {
;     ...
;   const float lt = l_run + __shfl_xor(l_run, 32);
;   const float inv = 1.f / lt;
;   const size_t rq = (size_t)(32 * w + l31);
; #pragma unroll
;   for (int d = 0; d < 2; ++d)
; #pragma unroll
;     for (int q = 0; q < 4; ++q) {
;       const int dv = 32 * d + 8 * q + 4 * h;
;       f32x4 g = unpack4(*(const u32x2*)(Pg + rq * NIN + dv));
;       f32x4 v = {o[d][4 * q] * inv * silu(g[0]), o[d][4 * q + 1] * inv * silu(g[1]), o[d][4 * q + 2] * inv * silu(g[2]), o[d][4 * q + 3] * inv * silu(g[3])};
;       *(u32x2*)(Yg + rq * 1024 + dv) = pack4(v);
;     }
.LBB0_31:
	s_waitcnt lgkmcnt(0)
	v_add_f32_e32 v0, v215, v0
	v_div_scale_f32 v66, s[4:5], v0, v0, 1.0
	v_rcp_f32_e32 v67, v66
	v_readlane_b32 s69, v255, 25
	s_add_i32 s64, s64, s69
	s_cmp_ge_u32 s64, s75
	v_fma_f32 v68, -v66, v67, 1.0
	v_fmac_f32_e32 v67, v68, v67
	v_div_scale_f32 v68, vcc, 1.0, v0, 1.0
	v_mul_f32_e32 v69, v68, v67
	v_fma_f32 v70, -v66, v69, v68
	v_fmac_f32_e32 v69, v70, v67
	v_fma_f32 v66, -v66, v69, v68
	v_div_fmas_f32 v66, v66, v67, v69
	v_mov_b64_e32 v[68:69], s[36:37]
	v_mad_u64_u32 v[68:69], s[4:5], v188, s11, v[68:69]
	v_div_fixup_f32 v66, v66, v0, 1.0
	v_mov_b32_e32 v0, v69
	v_mad_u64_u32 v[70:71], s[4:5], v189, s11, v[0:1]
	v_mov_b32_e32 v69, v70
	v_lshlrev_b32_e32 v0, 3, v187
	v_lshl_add_u64 v[68:69], v[68:69], 0, v[0:1]
	global_load_dwordx2 v[112:113], v[68:69], off
	global_load_dwordx2 v[114:115], v[68:69], off offset:16
	global_load_dwordx2 v[116:117], v[68:69], off offset:32
	global_load_dwordx2 v[118:119], v[68:69], off offset:48
	global_load_dwordx2 v[120:121], v[68:69], off offset:64
	global_load_dwordx2 v[122:123], v[68:69], off offset:80
	global_load_dwordx2 v[124:125], v[68:69], off offset:96
	global_load_dwordx2 v[126:127], v[68:69], off offset:112
	v_lshlrev_b64 v[70:71], 11, v[188:189]
	v_lshl_add_u64 v[70:71], s[40:41], 0, v[70:71]
	v_mov_b32_e32 v187, v202
	s_waitcnt vmcnt(0)
	v_mov_b32_e32 v72, v112
	v_mov_b32_e32 v73, v113
	v_lshlrev_b32_e32 v67, 16, v72
	v_and_b32_e32 v72, 0xffff0000, v72
	v_mul_f32_e32 v74, 0xbfb8aa3b, v67
	v_mul_f32_e32 v75, 0xbfb8aa3b, v72
	v_exp_f32_e32 v74, v74
	v_exp_f32_e32 v75, v75
	v_pk_mul_f32 v[50:51], v[66:67], v[50:51] op_sel_hi:[0,1]
	v_pk_add_f32 v[74:75], v[74:75], 1.0 op_sel_hi:[1,0]
	s_nop 0
	v_div_scale_f32 v76, s[4:5], v75, v75, v72
	v_rcp_f32_e32 v77, v76
	s_nop 0
	v_fma_f32 v78, -v76, v77, 1.0
	v_fmac_f32_e32 v77, v78, v77
	v_div_scale_f32 v78, vcc, v72, v75, v72
	v_mul_f32_e32 v79, v78, v77
	v_fma_f32 v80, -v76, v79, v78
	v_fmac_f32_e32 v79, v80, v77
	v_fma_f32 v76, -v76, v79, v78
	v_div_fmas_f32 v76, v76, v77, v79
	v_div_fixup_f32 v75, v76, v75, v72
	v_div_scale_f32 v72, s[4:5], v74, v74, v67
	v_rcp_f32_e32 v76, v72
	s_nop 0
	v_fma_f32 v77, -v72, v76, 1.0
	v_fmac_f32_e32 v76, v77, v76
	v_div_scale_f32 v77, vcc, v67, v74, v67
	v_mul_f32_e32 v78, v77, v76
	v_fma_f32 v79, -v72, v78, v77
	v_fmac_f32_e32 v78, v79, v76
	v_fma_f32 v72, -v72, v78, v77
	v_div_fmas_f32 v72, v72, v76, v78
	v_div_fixup_f32 v74, v72, v74, v67
	v_pk_mul_f32 v[50:51], v[50:51], v[74:75]
	v_lshlrev_b32_e32 v67, 16, v73
	v_and_b32_e32 v74, 0xffff0000, v73
	v_mul_f32_e32 v72, 0xbfb8aa3b, v67
	v_mul_f32_e32 v73, 0xbfb8aa3b, v74
	v_exp_f32_e32 v72, v72
	v_exp_f32_e32 v73, v73
	v_pk_mul_f32 v[52:53], v[66:67], v[52:53] op_sel_hi:[0,1]
	v_pk_add_f32 v[72:73], v[72:73], 1.0 op_sel_hi:[1,0]
	s_nop 0
	v_div_scale_f32 v75, s[4:5], v73, v73, v74
	v_rcp_f32_e32 v76, v75
	s_nop 0
	v_fma_f32 v77, -v75, v76, 1.0
	v_fmac_f32_e32 v76, v77, v76
	v_div_scale_f32 v77, vcc, v74, v73, v74
	v_mul_f32_e32 v78, v77, v76
	v_fma_f32 v79, -v75, v78, v77
	v_fmac_f32_e32 v78, v79, v76
	v_fma_f32 v75, -v75, v78, v77
	v_div_fmas_f32 v75, v75, v76, v78
	v_div_fixup_f32 v73, v75, v73, v74
	v_div_scale_f32 v74, s[4:5], v72, v72, v67
	v_rcp_f32_e32 v75, v74
	s_nop 0
	v_fma_f32 v76, -v74, v75, 1.0
	v_fmac_f32_e32 v75, v76, v75
	v_div_scale_f32 v76, vcc, v67, v72, v67
	v_mul_f32_e32 v77, v76, v75
	v_fma_f32 v78, -v74, v77, v76
	v_fmac_f32_e32 v77, v78, v75
	v_fma_f32 v74, -v74, v77, v76
	v_div_fmas_f32 v74, v74, v75, v77
	v_div_fixup_f32 v72, v74, v72, v67
	v_pk_mul_f32 v[72:73], v[52:53], v[72:73]
	v_cvt_pk_bf16_f32 v52, v50, v51
	v_cvt_pk_bf16_f32 v53, v72, v73
	v_lshl_add_u64 v[50:51], v[70:71], 0, v[0:1]
	global_store_dwordx2 v[50:51], v[52:53], off
	v_mov_b32_e32 v70, v114
	v_mov_b32_e32 v71, v115
	v_lshlrev_b32_e32 v0, 16, v70
	v_and_b32_e32 v67, 0xffff0000, v70
	v_mul_f32_e32 v52, 0xbfb8aa3b, v0
	v_mul_f32_e32 v53, 0xbfb8aa3b, v67
	v_exp_f32_e32 v52, v52
	v_exp_f32_e32 v53, v53
	v_pk_mul_f32 v[54:55], v[66:67], v[54:55] op_sel_hi:[0,1]
	v_pk_add_f32 v[52:53], v[52:53], 1.0 op_sel_hi:[1,0]
	s_nop 0
	v_div_scale_f32 v70, s[4:5], v53, v53, v67
	v_rcp_f32_e32 v72, v70
	s_nop 0
	v_fma_f32 v73, -v70, v72, 1.0
	v_fmac_f32_e32 v72, v73, v72
	v_div_scale_f32 v73, vcc, v67, v53, v67
	v_mul_f32_e32 v74, v73, v72
	v_fma_f32 v75, -v70, v74, v73
	v_fmac_f32_e32 v74, v75, v72
	v_fma_f32 v70, -v70, v74, v73
	v_div_fmas_f32 v70, v70, v72, v74
	v_div_fixup_f32 v53, v70, v53, v67
	v_div_scale_f32 v67, s[4:5], v52, v52, v0
	v_rcp_f32_e32 v70, v67
	s_nop 0
	v_fma_f32 v72, -v67, v70, 1.0
	v_fmac_f32_e32 v70, v72, v70
	v_div_scale_f32 v72, vcc, v0, v52, v0
	v_mul_f32_e32 v73, v72, v70
	v_fma_f32 v74, -v67, v73, v72
	v_fmac_f32_e32 v73, v74, v70
	v_fma_f32 v67, -v67, v73, v72
	v_div_fmas_f32 v67, v67, v70, v73
	v_div_fixup_f32 v52, v67, v52, v0
	v_lshlrev_b32_e32 v0, 16, v71
	v_pk_mul_f32 v[52:53], v[54:55], v[52:53]
	v_and_b32_e32 v67, 0xffff0000, v71
	v_mul_f32_e32 v54, 0xbfb8aa3b, v0
	v_exp_f32_e32 v70, v54
	v_pk_mul_f32 v[54:55], v[66:67], v[56:57] op_sel_hi:[0,1]
	v_mul_f32_e32 v56, 0xbfb8aa3b, v67
	v_exp_f32_e32 v71, v56
	v_cvt_pk_bf16_f32 v52, v52, v53
	v_pk_add_f32 v[56:57], v[70:71], 1.0 op_sel_hi:[1,0]
	s_nop 0
	v_div_scale_f32 v70, s[4:5], v57, v57, v67
	v_rcp_f32_e32 v71, v70
	s_nop 0
	v_fma_f32 v72, -v70, v71, 1.0
	v_fmac_f32_e32 v71, v72, v71
	v_div_scale_f32 v72, vcc, v67, v57, v67
	v_mul_f32_e32 v73, v72, v71
	v_fma_f32 v74, -v70, v73, v72
	v_fmac_f32_e32 v73, v74, v71
	v_fma_f32 v70, -v70, v73, v72
	v_div_fmas_f32 v70, v70, v71, v73
	v_div_fixup_f32 v57, v70, v57, v67
	v_div_scale_f32 v67, s[4:5], v56, v56, v0
; DI float silu(float x) { return x / (1.f + __expf(-x)); }
; DI f32x4 unpack4(u32x2 v) { f32x4 r = {bflo(v.x), bfhi(v.x), bflo(v.y), bfhi(v.y)}; return r; }
; DI u32x2 pack4(f32x4 v) { u32x2 r = {cvtpk(v[0], v[1]), cvtpk(v[2], v[3])}; return r; }
; template <int DQK, bool STATIC>
; DI void attn_item8(const bf16_t* __restrict__ Q, const bf16_t* __restrict__ Kp, const bf16_t* __restrict__ Vt, int nkeys, char* lds,
;                   const bf16_t* __restrict__ Pg, bf16_t* __restrict__ Yg  , float mfix) {
;     ...
; #pragma unroll
;   for (int d = 0; d < 2; ++d)
; #pragma unroll
;     for (int q = 0; q < 4; ++q) {
;       const int dv = 32 * d + 8 * q + 4 * h;
;       f32x4 g = unpack4(*(const u32x2*)(Pg + rq * NIN + dv));
;       f32x4 v = {o[d][4 * q] * inv * silu(g[0]), o[d][4 * q + 1] * inv * silu(g[1]), o[d][4 * q + 2] * inv * silu(g[2]), o[d][4 * q + 3] * inv * silu(g[3])};
;       *(u32x2*)(Yg + rq * 1024 + dv) = pack4(v);
;     }
	v_rcp_f32_e32 v70, v67
	s_nop 0
	v_fma_f32 v71, -v67, v70, 1.0
	v_fmac_f32_e32 v70, v71, v70
	v_div_scale_f32 v71, vcc, v0, v56, v0
	v_mul_f32_e32 v72, v71, v70
	v_fma_f32 v73, -v67, v72, v71
	v_fmac_f32_e32 v72, v73, v70
	v_fma_f32 v67, -v67, v72, v71
	v_div_fmas_f32 v67, v67, v70, v72
	v_div_fixup_f32 v56, v67, v56, v0
	v_pk_mul_f32 v[54:55], v[54:55], v[56:57]
	v_pk_mul_f32 v[56:57], v[66:67], v[58:59] op_sel_hi:[0,1]
	v_cvt_pk_bf16_f32 v53, v54, v55
	global_store_dwordx2 v[50:51], v[52:53], off offset:16
	v_mov_b32_e32 v54, v116
	v_mov_b32_e32 v55, v117
	v_lshlrev_b32_e32 v0, 16, v54
	v_and_b32_e32 v54, 0xffff0000, v54
	v_mul_f32_e32 v52, 0xbfb8aa3b, v0
	v_mul_f32_e32 v53, 0xbfb8aa3b, v54
	v_exp_f32_e32 v52, v52
	v_exp_f32_e32 v53, v53
	s_nop 0
	v_pk_add_f32 v[52:53], v[52:53], 1.0 op_sel_hi:[1,0]
	s_nop 0
	v_div_scale_f32 v58, s[4:5], v53, v53, v54
	v_rcp_f32_e32 v59, v58
	s_nop 0
	v_fma_f32 v67, -v58, v59, 1.0
	v_fmac_f32_e32 v59, v67, v59
	v_div_scale_f32 v67, vcc, v54, v53, v54
	v_mul_f32_e32 v70, v67, v59
	v_fma_f32 v71, -v58, v70, v67
	v_fmac_f32_e32 v70, v71, v59
	v_fma_f32 v58, -v58, v70, v67
	v_div_fmas_f32 v58, v58, v59, v70
	v_div_fixup_f32 v53, v58, v53, v54
	v_div_scale_f32 v54, s[4:5], v52, v52, v0
	v_rcp_f32_e32 v58, v54
	s_nop 0
	v_fma_f32 v59, -v54, v58, 1.0
	v_fmac_f32_e32 v58, v59, v58
	v_div_scale_f32 v59, vcc, v0, v52, v0
	v_mul_f32_e32 v67, v59, v58
	v_fma_f32 v70, -v54, v67, v59
	v_fmac_f32_e32 v67, v70, v58
	v_fma_f32 v54, -v54, v67, v59
	v_div_fmas_f32 v54, v54, v58, v67
	v_div_fixup_f32 v52, v54, v52, v0
	v_lshlrev_b32_e32 v0, 16, v55
	v_and_b32_e32 v58, 0xffff0000, v55
	v_pk_mul_f32 v[52:53], v[56:57], v[52:53]
	v_mul_f32_e32 v54, 0xbfb8aa3b, v0
	v_mul_f32_e32 v57, 0xbfb8aa3b, v58
	v_exp_f32_e32 v56, v54
	v_exp_f32_e32 v57, v57
	v_pk_mul_f32 v[54:55], v[66:67], v[60:61] op_sel_hi:[0,1]
	v_cvt_pk_bf16_f32 v52, v52, v53
	v_pk_add_f32 v[56:57], v[56:57], 1.0 op_sel_hi:[1,0]
	s_nop 0
	v_div_scale_f32 v59, s[4:5], v57, v57, v58
	v_rcp_f32_e32 v60, v59
	s_nop 0
	v_fma_f32 v61, -v59, v60, 1.0
	v_fmac_f32_e32 v60, v61, v60
	v_div_scale_f32 v61, vcc, v58, v57, v58
	v_mul_f32_e32 v67, v61, v60
	v_fma_f32 v70, -v59, v67, v61
	v_fmac_f32_e32 v67, v70, v60
	v_fma_f32 v59, -v59, v67, v61
	v_div_fmas_f32 v59, v59, v60, v67
	v_div_fixup_f32 v57, v59, v57, v58
	v_div_scale_f32 v58, s[4:5], v56, v56, v0
	v_rcp_f32_e32 v59, v58
	s_nop 0
	v_fma_f32 v60, -v58, v59, 1.0
	v_fmac_f32_e32 v59, v60, v59
	v_div_scale_f32 v60, vcc, v0, v56, v0
	v_mul_f32_e32 v61, v60, v59
	v_fma_f32 v67, -v58, v61, v60
	v_fmac_f32_e32 v61, v67, v59
	v_fma_f32 v58, -v58, v61, v60
	v_div_fmas_f32 v58, v58, v59, v61
	v_div_fixup_f32 v56, v58, v56, v0
	v_pk_mul_f32 v[54:55], v[54:55], v[56:57]
	v_pk_mul_f32 v[56:57], v[66:67], v[62:63] op_sel_hi:[0,1]
	v_cvt_pk_bf16_f32 v53, v54, v55
	global_store_dwordx2 v[50:51], v[52:53], off offset:32
	v_mov_b32_e32 v54, v118
	v_mov_b32_e32 v55, v119
	v_pk_mul_f32 v[34:35], v[66:67], v[34:35] op_sel_hi:[0,1]
	v_pk_mul_f32 v[36:37], v[66:67], v[36:37] op_sel_hi:[0,1]
	v_pk_mul_f32 v[38:39], v[66:67], v[38:39] op_sel_hi:[0,1]
	v_lshlrev_b32_e32 v0, 16, v54
	v_and_b32_e32 v54, 0xffff0000, v54
	v_mul_f32_e32 v52, 0xbfb8aa3b, v0
	v_mul_f32_e32 v53, 0xbfb8aa3b, v54
	v_exp_f32_e32 v52, v52
	v_exp_f32_e32 v53, v53
	s_nop 0
	v_pk_add_f32 v[52:53], v[52:53], 1.0 op_sel_hi:[1,0]
	s_nop 0
	v_div_scale_f32 v58, s[4:5], v53, v53, v54
	v_rcp_f32_e32 v59, v58
	s_nop 0
	v_fma_f32 v60, -v58, v59, 1.0
	v_fmac_f32_e32 v59, v60, v59
	v_div_scale_f32 v60, vcc, v54, v53, v54
	v_mul_f32_e32 v61, v60, v59
	v_fma_f32 v62, -v58, v61, v60
	v_fmac_f32_e32 v61, v62, v59
	v_fma_f32 v58, -v58, v61, v60
	v_div_fmas_f32 v58, v58, v59, v61
	v_div_fixup_f32 v53, v58, v53, v54
	v_div_scale_f32 v54, s[4:5], v52, v52, v0
	v_rcp_f32_e32 v58, v54
	s_nop 0
	v_fma_f32 v59, -v54, v58, 1.0
	v_fmac_f32_e32 v58, v59, v58
	v_div_scale_f32 v59, vcc, v0, v52, v0
	v_mul_f32_e32 v60, v59, v58
	v_fma_f32 v61, -v54, v60, v59
	v_fmac_f32_e32 v60, v61, v58
	v_fma_f32 v54, -v54, v60, v59
	v_div_fmas_f32 v54, v54, v58, v60
	v_div_fixup_f32 v52, v54, v52, v0
	v_lshlrev_b32_e32 v0, 16, v55
	v_and_b32_e32 v58, 0xffff0000, v55
	v_pk_mul_f32 v[52:53], v[56:57], v[52:53]
	v_mul_f32_e32 v54, 0xbfb8aa3b, v0
	v_mul_f32_e32 v57, 0xbfb8aa3b, v58
	v_exp_f32_e32 v56, v54
	v_exp_f32_e32 v57, v57
	v_pk_mul_f32 v[54:55], v[66:67], v[64:65] op_sel_hi:[0,1]
	v_cvt_pk_bf16_f32 v52, v52, v53
	v_pk_add_f32 v[56:57], v[56:57], 1.0 op_sel_hi:[1,0]
	s_nop 0
	v_div_scale_f32 v59, s[4:5], v57, v57, v58
	v_rcp_f32_e32 v60, v59
	s_nop 0
	v_fma_f32 v61, -v59, v60, 1.0
	v_fmac_f32_e32 v60, v61, v60
	v_div_scale_f32 v61, vcc, v58, v57, v58
	v_mul_f32_e32 v62, v61, v60
	v_fma_f32 v63, -v59, v62, v61
	v_fmac_f32_e32 v62, v63, v60
	v_fma_f32 v59, -v59, v62, v61
	v_div_fmas_f32 v59, v59, v60, v62
	v_div_fixup_f32 v57, v59, v57, v58
	v_div_scale_f32 v58, s[4:5], v56, v56, v0
	v_rcp_f32_e32 v59, v58
	s_nop 0
	v_fma_f32 v60, -v58, v59, 1.0
	v_fmac_f32_e32 v59, v60, v59
	v_div_scale_f32 v60, vcc, v0, v56, v0
	v_mul_f32_e32 v61, v60, v59
	v_fma_f32 v62, -v58, v61, v60
	v_fmac_f32_e32 v61, v62, v59
	v_fma_f32 v58, -v58, v61, v60
	v_div_fmas_f32 v58, v58, v59, v61
	v_div_fixup_f32 v56, v58, v56, v0
	v_pk_mul_f32 v[54:55], v[54:55], v[56:57]
	s_nop 0
	v_cvt_pk_bf16_f32 v53, v54, v55
	global_store_dwordx2 v[50:51], v[52:53], off offset:48
	v_mov_b32_e32 v52, v120
	v_mov_b32_e32 v53, v121
	v_lshlrev_b32_e32 v0, 16, v52
	v_and_b32_e32 v52, 0xffff0000, v52
	v_mul_f32_e32 v54, 0xbfb8aa3b, v0
	v_mul_f32_e32 v55, 0xbfb8aa3b, v52
	v_exp_f32_e32 v54, v54
	v_exp_f32_e32 v55, v55
	s_nop 0
	v_pk_add_f32 v[54:55], v[54:55], 1.0 op_sel_hi:[1,0]
; DI float silu(float x) { return x / (1.f + __expf(-x)); }
; DI f32x4 unpack4(u32x2 v) { f32x4 r = {bflo(v.x), bfhi(v.x), bflo(v.y), bfhi(v.y)}; return r; }
; DI u32x2 pack4(f32x4 v) { u32x2 r = {cvtpk(v[0], v[1]), cvtpk(v[2], v[3])}; return r; }
; template <int DQK, bool STATIC>
; DI void attn_item8(const bf16_t* __restrict__ Q, const bf16_t* __restrict__ Kp, const bf16_t* __restrict__ Vt, int nkeys, char* lds,
;                   const bf16_t* __restrict__ Pg, bf16_t* __restrict__ Yg  , float mfix) {
;     ...
; #pragma unroll
;   for (int d = 0; d < 2; ++d)
; #pragma unroll
;     for (int q = 0; q < 4; ++q) {
;       const int dv = 32 * d + 8 * q + 4 * h;
;       f32x4 g = unpack4(*(const u32x2*)(Pg + rq * NIN + dv));
;       f32x4 v = {o[d][4 * q] * inv * silu(g[0]), o[d][4 * q + 1] * inv * silu(g[1]), o[d][4 * q + 2] * inv * silu(g[2]), o[d][4 * q + 3] * inv * silu(g[3])};
;       *(u32x2*)(Yg + rq * 1024 + dv) = pack4(v);
;     }
	s_nop 0
	v_div_scale_f32 v56, s[4:5], v55, v55, v52
	v_rcp_f32_e32 v57, v56
	s_nop 0
	v_fma_f32 v58, -v56, v57, 1.0
	v_fmac_f32_e32 v57, v58, v57
	v_div_scale_f32 v58, vcc, v52, v55, v52
	v_mul_f32_e32 v59, v58, v57
	v_fma_f32 v60, -v56, v59, v58
	v_fmac_f32_e32 v59, v60, v57
	v_fma_f32 v56, -v56, v59, v58
	v_div_fmas_f32 v56, v56, v57, v59
	v_div_fixup_f32 v55, v56, v55, v52
	v_div_scale_f32 v52, s[4:5], v54, v54, v0
	v_rcp_f32_e32 v56, v52
	s_nop 0
	v_fma_f32 v57, -v52, v56, 1.0
	v_fmac_f32_e32 v56, v57, v56
	v_div_scale_f32 v57, vcc, v0, v54, v0
	v_mul_f32_e32 v58, v57, v56
	v_fma_f32 v59, -v52, v58, v57
	v_fmac_f32_e32 v58, v59, v56
	v_fma_f32 v52, -v52, v58, v57
	v_div_fmas_f32 v52, v52, v56, v58
	v_div_fixup_f32 v54, v52, v54, v0
	v_pk_mul_f32 v[34:35], v[34:35], v[54:55]
	v_lshlrev_b32_e32 v0, 16, v53
	v_and_b32_e32 v54, 0xffff0000, v53
	v_mul_f32_e32 v52, 0xbfb8aa3b, v0
	v_mul_f32_e32 v53, 0xbfb8aa3b, v54
	v_exp_f32_e32 v52, v52
	v_exp_f32_e32 v53, v53
	v_cvt_pk_bf16_f32 v34, v34, v35
	v_pk_add_f32 v[52:53], v[52:53], 1.0 op_sel_hi:[1,0]
	s_nop 0
	v_div_scale_f32 v55, s[4:5], v53, v53, v54
	v_rcp_f32_e32 v56, v55
	s_nop 0
	v_fma_f32 v57, -v55, v56, 1.0
	v_fmac_f32_e32 v56, v57, v56
	v_div_scale_f32 v57, vcc, v54, v53, v54
	v_mul_f32_e32 v58, v57, v56
	v_fma_f32 v59, -v55, v58, v57
	v_fmac_f32_e32 v58, v59, v56
	v_fma_f32 v55, -v55, v58, v57
	v_div_fmas_f32 v55, v55, v56, v58
	v_div_fixup_f32 v53, v55, v53, v54
	v_div_scale_f32 v54, s[4:5], v52, v52, v0
	v_rcp_f32_e32 v55, v54
	s_nop 0
	v_fma_f32 v56, -v54, v55, 1.0
	v_fmac_f32_e32 v55, v56, v55
	v_div_scale_f32 v56, vcc, v0, v52, v0
	v_mul_f32_e32 v57, v56, v55
	v_fma_f32 v58, -v54, v57, v56
	v_fmac_f32_e32 v57, v58, v55
	v_fma_f32 v54, -v54, v57, v56
	v_div_fmas_f32 v54, v54, v55, v57
	v_div_fixup_f32 v52, v54, v52, v0
	v_pk_mul_f32 v[36:37], v[36:37], v[52:53]
	s_nop 0
	v_cvt_pk_bf16_f32 v35, v36, v37
	global_store_dwordx2 v[50:51], v[34:35], off offset:64
	v_mov_b32_e32 v36, v122
	v_mov_b32_e32 v37, v123
	v_lshlrev_b32_e32 v0, 16, v36
	v_and_b32_e32 v36, 0xffff0000, v36
	v_mul_f32_e32 v34, 0xbfb8aa3b, v0
	v_mul_f32_e32 v35, 0xbfb8aa3b, v36
	v_exp_f32_e32 v34, v34
	v_exp_f32_e32 v35, v35
	s_nop 0
	v_pk_add_f32 v[34:35], v[34:35], 1.0 op_sel_hi:[1,0]
	s_nop 0
	v_div_scale_f32 v52, s[4:5], v35, v35, v36
	v_rcp_f32_e32 v53, v52
	s_nop 0
	v_fma_f32 v54, -v52, v53, 1.0
	v_fmac_f32_e32 v53, v54, v53
	v_div_scale_f32 v54, vcc, v36, v35, v36
	v_mul_f32_e32 v55, v54, v53
	v_fma_f32 v56, -v52, v55, v54
	v_fmac_f32_e32 v55, v56, v53
	v_fma_f32 v52, -v52, v55, v54
	v_div_fmas_f32 v52, v52, v53, v55
	v_div_fixup_f32 v35, v52, v35, v36
	v_div_scale_f32 v36, s[4:5], v34, v34, v0
	v_rcp_f32_e32 v52, v36
	s_nop 0
	v_fma_f32 v53, -v36, v52, 1.0
	v_fmac_f32_e32 v52, v53, v52
	v_div_scale_f32 v53, vcc, v0, v34, v0
	v_mul_f32_e32 v54, v53, v52
	v_fma_f32 v55, -v36, v54, v53
	v_fmac_f32_e32 v54, v55, v52
	v_fma_f32 v36, -v36, v54, v53
	v_div_fmas_f32 v36, v36, v52, v54
	v_div_fixup_f32 v34, v36, v34, v0
	v_lshlrev_b32_e32 v0, 16, v37
	v_and_b32_e32 v52, 0xffff0000, v37
	v_pk_mul_f32 v[34:35], v[38:39], v[34:35]
	v_mul_f32_e32 v36, 0xbfb8aa3b, v0
	v_mul_f32_e32 v39, 0xbfb8aa3b, v52
	v_exp_f32_e32 v38, v36
	v_exp_f32_e32 v39, v39
	v_pk_mul_f32 v[36:37], v[66:67], v[40:41] op_sel_hi:[0,1]
	v_cvt_pk_bf16_f32 v34, v34, v35
	v_pk_add_f32 v[38:39], v[38:39], 1.0 op_sel_hi:[1,0]
	s_nop 0
	v_div_scale_f32 v40, s[4:5], v39, v39, v52
	v_rcp_f32_e32 v41, v40
	s_nop 0
	v_fma_f32 v53, -v40, v41, 1.0
	v_fmac_f32_e32 v41, v53, v41
	v_div_scale_f32 v53, vcc, v52, v39, v52
	v_mul_f32_e32 v54, v53, v41
	v_fma_f32 v55, -v40, v54, v53
	v_fmac_f32_e32 v54, v55, v41
	v_fma_f32 v40, -v40, v54, v53
	v_div_fmas_f32 v40, v40, v41, v54
	v_div_fixup_f32 v39, v40, v39, v52
	v_div_scale_f32 v40, s[4:5], v38, v38, v0
	v_rcp_f32_e32 v41, v40
	s_nop 0
	v_fma_f32 v52, -v40, v41, 1.0
	v_fmac_f32_e32 v41, v52, v41
	v_div_scale_f32 v52, vcc, v0, v38, v0
	v_mul_f32_e32 v53, v52, v41
	v_fma_f32 v54, -v40, v53, v52
	v_fmac_f32_e32 v53, v54, v41
	v_fma_f32 v40, -v40, v53, v52
	v_div_fmas_f32 v40, v40, v41, v53
	v_div_fixup_f32 v38, v40, v38, v0
	v_pk_mul_f32 v[36:37], v[36:37], v[38:39]
	v_pk_mul_f32 v[38:39], v[66:67], v[42:43] op_sel_hi:[0,1]
	v_cvt_pk_bf16_f32 v35, v36, v37
	global_store_dwordx2 v[50:51], v[34:35], off offset:80
	v_mov_b32_e32 v36, v124
	v_mov_b32_e32 v37, v125
	v_lshlrev_b32_e32 v0, 16, v36
	v_and_b32_e32 v36, 0xffff0000, v36
	v_mul_f32_e32 v34, 0xbfb8aa3b, v0
	v_mul_f32_e32 v35, 0xbfb8aa3b, v36
; DI float silu(float x) { return x / (1.f + __expf(-x)); }
; DI f32x4 unpack4(u32x2 v) { f32x4 r = {bflo(v.x), bfhi(v.x), bflo(v.y), bfhi(v.y)}; return r; }
; DI u32x2 pack4(f32x4 v) { u32x2 r = {cvtpk(v[0], v[1]), cvtpk(v[2], v[3])}; return r; }
; template <int DQK, bool STATIC>
; DI void attn_item8(const bf16_t* __restrict__ Q, const bf16_t* __restrict__ Kp, const bf16_t* __restrict__ Vt, int nkeys, char* lds,
;                   const bf16_t* __restrict__ Pg, bf16_t* __restrict__ Yg  , float mfix) {
;     ...
; #pragma unroll
;   for (int d = 0; d < 2; ++d)
; #pragma unroll
;     for (int q = 0; q < 4; ++q) {
;       const int dv = 32 * d + 8 * q + 4 * h;
;       f32x4 g = unpack4(*(const u32x2*)(Pg + rq * NIN + dv));
;       f32x4 v = {o[d][4 * q] * inv * silu(g[0]), o[d][4 * q + 1] * inv * silu(g[1]), o[d][4 * q + 2] * inv * silu(g[2]), o[d][4 * q + 3] * inv * silu(g[3])};
;       *(u32x2*)(Yg + rq * 1024 + dv) = pack4(v);
;     }
; DI void phase_mix(KP p, int l, char* lds) {
;     ...
;     for (int it = lbw; it < nW; it += nlbw) {
	v_exp_f32_e32 v34, v34
	v_exp_f32_e32 v35, v35
	s_nop 0
	v_pk_add_f32 v[34:35], v[34:35], 1.0 op_sel_hi:[1,0]
	s_nop 0
	v_div_scale_f32 v40, s[4:5], v35, v35, v36
	v_rcp_f32_e32 v41, v40
	s_nop 0
	v_fma_f32 v42, -v40, v41, 1.0
	v_fmac_f32_e32 v41, v42, v41
	v_div_scale_f32 v42, vcc, v36, v35, v36
	v_mul_f32_e32 v43, v42, v41
	v_fma_f32 v52, -v40, v43, v42
	v_fmac_f32_e32 v43, v52, v41
	v_fma_f32 v40, -v40, v43, v42
	v_div_fmas_f32 v40, v40, v41, v43
	v_div_fixup_f32 v35, v40, v35, v36
	v_div_scale_f32 v36, s[4:5], v34, v34, v0
	v_rcp_f32_e32 v40, v36
	s_nop 0
	v_fma_f32 v41, -v36, v40, 1.0
	v_fmac_f32_e32 v40, v41, v40
	v_div_scale_f32 v41, vcc, v0, v34, v0
	v_mul_f32_e32 v42, v41, v40
	v_fma_f32 v43, -v36, v42, v41
	v_fmac_f32_e32 v42, v43, v40
	v_fma_f32 v36, -v36, v42, v41
	v_div_fmas_f32 v36, v36, v40, v42
	v_div_fixup_f32 v34, v36, v34, v0
	v_lshlrev_b32_e32 v0, 16, v37
	v_and_b32_e32 v40, 0xffff0000, v37
	v_pk_mul_f32 v[34:35], v[38:39], v[34:35]
	v_mul_f32_e32 v36, 0xbfb8aa3b, v0
	v_mul_f32_e32 v39, 0xbfb8aa3b, v40
	v_exp_f32_e32 v38, v36
	v_exp_f32_e32 v39, v39
	v_pk_mul_f32 v[36:37], v[66:67], v[44:45] op_sel_hi:[0,1]
	v_cvt_pk_bf16_f32 v34, v34, v35
	v_pk_add_f32 v[38:39], v[38:39], 1.0 op_sel_hi:[1,0]
	s_nop 0
	v_div_scale_f32 v41, s[4:5], v39, v39, v40
	v_rcp_f32_e32 v42, v41
	s_nop 0
	v_fma_f32 v43, -v41, v42, 1.0
	v_fmac_f32_e32 v42, v43, v42
	v_div_scale_f32 v43, vcc, v40, v39, v40
	v_mul_f32_e32 v44, v43, v42
	v_fma_f32 v45, -v41, v44, v43
	v_fmac_f32_e32 v44, v45, v42
	v_fma_f32 v41, -v41, v44, v43
	v_div_fmas_f32 v41, v41, v42, v44
	v_div_fixup_f32 v39, v41, v39, v40
	v_div_scale_f32 v40, s[4:5], v38, v38, v0
	v_rcp_f32_e32 v41, v40
	s_nop 0
	v_fma_f32 v42, -v40, v41, 1.0
	v_fmac_f32_e32 v41, v42, v41
	v_div_scale_f32 v42, vcc, v0, v38, v0
	v_mul_f32_e32 v43, v42, v41
	v_fma_f32 v44, -v40, v43, v42
	v_fmac_f32_e32 v43, v44, v41
	v_fma_f32 v40, -v40, v43, v42
	v_div_fmas_f32 v40, v40, v41, v43
	v_div_fixup_f32 v38, v40, v38, v0
	v_pk_mul_f32 v[36:37], v[36:37], v[38:39]
	v_pk_mul_f32 v[38:39], v[66:67], v[46:47] op_sel_hi:[0,1]
	v_cvt_pk_bf16_f32 v35, v36, v37
	global_store_dwordx2 v[50:51], v[34:35], off offset:96
	v_mov_b32_e32 v34, v126
	v_mov_b32_e32 v35, v127
	v_lshlrev_b32_e32 v0, 16, v34
	v_and_b32_e32 v34, 0xffff0000, v34
	v_mul_f32_e32 v36, 0xbfb8aa3b, v0
	v_mul_f32_e32 v37, 0xbfb8aa3b, v34
	v_exp_f32_e32 v36, v36
	v_exp_f32_e32 v37, v37
	s_nop 0
	v_pk_add_f32 v[36:37], v[36:37], 1.0 op_sel_hi:[1,0]
	s_nop 0
	v_div_scale_f32 v40, s[4:5], v37, v37, v34
	v_rcp_f32_e32 v41, v40
	s_nop 0
	v_fma_f32 v42, -v40, v41, 1.0
	v_fmac_f32_e32 v41, v42, v41
	v_div_scale_f32 v42, vcc, v34, v37, v34
	v_mul_f32_e32 v43, v42, v41
	v_fma_f32 v44, -v40, v43, v42
	v_fmac_f32_e32 v43, v44, v41
	v_fma_f32 v40, -v40, v43, v42
	v_div_fmas_f32 v40, v40, v41, v43
	v_div_fixup_f32 v37, v40, v37, v34
	v_div_scale_f32 v34, s[4:5], v36, v36, v0
	v_rcp_f32_e32 v40, v34
	s_nop 0
	v_fma_f32 v41, -v34, v40, 1.0
	v_fmac_f32_e32 v40, v41, v40
	v_div_scale_f32 v41, vcc, v0, v36, v0
	v_mul_f32_e32 v42, v41, v40
	v_fma_f32 v43, -v34, v42, v41
	v_fmac_f32_e32 v42, v43, v40
	v_fma_f32 v34, -v34, v42, v41
	v_div_fmas_f32 v34, v34, v40, v42
	v_div_fixup_f32 v36, v34, v36, v0
	v_lshlrev_b32_e32 v0, 16, v35
	v_and_b32_e32 v40, 0xffff0000, v35
	v_mul_f32_e32 v34, 0xbfb8aa3b, v0
	v_mul_f32_e32 v35, 0xbfb8aa3b, v40
	v_exp_f32_e32 v34, v34
	v_exp_f32_e32 v35, v35
	v_pk_mul_f32 v[36:37], v[38:39], v[36:37]
	v_pk_mul_f32 v[38:39], v[66:67], v[48:49] op_sel_hi:[0,1]
	v_cvt_pk_bf16_f32 v36, v36, v37
	v_pk_add_f32 v[34:35], v[34:35], 1.0 op_sel_hi:[1,0]
	s_nop 0
	v_div_scale_f32 v41, s[4:5], v35, v35, v40
	v_rcp_f32_e32 v42, v41
	s_nop 0
	v_fma_f32 v43, -v41, v42, 1.0
	v_fmac_f32_e32 v42, v43, v42
	v_div_scale_f32 v43, vcc, v40, v35, v40
	v_mul_f32_e32 v44, v43, v42
	v_fma_f32 v45, -v41, v44, v43
	v_fmac_f32_e32 v44, v45, v42
	v_fma_f32 v41, -v41, v44, v43
	v_div_fmas_f32 v41, v41, v42, v44
	v_div_fixup_f32 v35, v41, v35, v40
	v_div_scale_f32 v40, s[4:5], v34, v34, v0
	v_rcp_f32_e32 v41, v40
	s_nop 0
	v_fma_f32 v42, -v40, v41, 1.0
	v_fmac_f32_e32 v41, v42, v41
	v_div_scale_f32 v42, vcc, v0, v34, v0
	v_mul_f32_e32 v43, v42, v41
	v_fma_f32 v44, -v40, v43, v42
	v_fmac_f32_e32 v43, v44, v41
	v_fma_f32 v40, -v40, v43, v42
	v_div_fmas_f32 v40, v40, v41, v43
	v_div_fixup_f32 v34, v40, v34, v0
	v_pk_mul_f32 v[34:35], v[38:39], v[34:35]
	s_nop 0
	v_cvt_pk_bf16_f32 v37, v34, v35
	global_store_dwordx2 v[50:51], v[36:37], off offset:112
	s_cbranch_scc1 .LBB0_123

; template <class Epi>
; DI void gemm256(const bf16_t* __restrict__ A, int lda, const bf16_t* __restrict__ Bt, int ldb, int K, char* lds, Epi epi) {
;     ...
;   float* ct = (float*)lds;
; #pragma unroll
;   for (int ai = 0; ai < 2; ++ai) {
;     __syncthreads();
; #pragma unroll
;     for (int bj = 0; bj < 2; ++bj)
; #pragma unroll
;       for (int m = 0; m < 4; ++m)
; #pragma unroll
;         for (int n = 0; n < 2; ++n)
; #pragma unroll
;           for (int j = 0; j < 4; ++j) ct[(wr * 64 + m * 16 + fq * 4 + j) * 260 + bj * 128 + wc * 32 + n * 16 + fr] = acc[ai][bj][m][n][j];
;     __syncthreads();
; #pragma unroll 2
;     for (int it = 0; it < 16; ++it) {
;       const int idx = it * NTHR + tid; const int row = idx >> 6, c4 = (idx & 63) * 4;
;       f32x4 v = *(const f32x4*)(ct + row * 260 + c4);
;       epi(ai * 128 + row, c4, v);
;     }
; DI void phase_outproj(KP p, int l, char* lds) {
;     ...
;       gemm256(Y + (size_t)m0 * 1024, 1024, wo + (size_t)n0 * 1024, 1024, 1024, lds, [&](int m, int n, f32x4 v) {
;         const size_t o = (size_t)m * 1024 + n0 + n;
;         f32x4 xv = __builtin_nontemporal_load((const f32x4*)(src + o)), g = *(const f32x4*)(gt + n0 + n);
;         f32x4 r = {xv[0] + g[0] * v[0], xv[1] + g[1] * v[1], xv[2] + g[2] * v[2], xv[3] + g[3] * v[3]};
;         __builtin_nontemporal_store(r, (f32x4*)(dst + o)); });
.LBB0_349:
	s_or_b64 exec, exec, s[18:19]
	v_lshlrev_b32_e32 v0, 6, v141
	v_lshl_or_b32 v131, v144, 2, v0
	v_lshl_add_u32 v132, v142, 7, 0
	v_lshlrev_b32_e32 v133, 2, v145
	v_mul_lo_u32 v131, v131, s9
	v_add3_u32 v131, v132, v133, v131
	s_waitcnt vmcnt(0)
	s_barrier
	ds_write2_b32 v131, v114, v126 offset1:16
	v_add_u32_e32 v114, 0x400, v131
	ds_write2_b32 v114, v115, v127 offset0:4 offset1:20
	v_add_u32_e32 v115, 0x800, v131
	ds_write2_b32 v115, v116, v128 offset0:8 offset1:24
	v_add_u32_e32 v116, 0xc00, v131
	s_mov_b32 s5, s3
	ds_write2_b32 v116, v117, v129 offset0:12 offset1:28
	v_add_u32_e32 v117, 0x4000, v131
	s_lshl_b32 s2, s50, 20
	s_lshl_b64 s[18:19], s[4:5], 23
	ds_write2_b32 v117, v82, v94 offset0:64 offset1:80
	v_add_u32_e32 v82, 0x4400, v131
	s_or_b32 s2, s18, s2
	ds_write2_b32 v82, v83, v95 offset0:68 offset1:84
	v_add_u32_e32 v83, 0x4800, v131
	s_add_u32 s48, s44, s2
	ds_write2_b32 v83, v84, v96 offset0:72 offset1:88
	v_add_u32_e32 v84, 0x4c00, v131
	s_addc_u32 s49, s45, s19
	ds_write2_b32 v84, v85, v97 offset0:76 offset1:92
	v_add_u32_e32 v85, 0x8000, v131
	s_add_u32 s50, s46, s2
	ds_write2_b32 v85, v74, v78 offset0:128 offset1:144
	v_add_u32_e32 v74, 0x8400, v131
	s_addc_u32 s51, s47, s19
	s_mul_hi_u32 s2, s4, 0x3000
	s_mulk_i32 s4, 0x3000
	ds_write2_b32 v74, v75, v79 offset0:132 offset1:148
	v_add_u32_e32 v75, 0x8800, v131
	s_add_u32 s4, s54, s4
	ds_write2_b32 v75, v76, v80 offset0:136 offset1:152
	v_add_u32_e32 v76, 0x8c00, v131
	s_addc_u32 s2, s55, s2
	ds_write2_b32 v76, v77, v81 offset0:140 offset1:156
	v_add_u32_e32 v77, 0xc000, v131
	s_lshl_b32 s5, s65, 2
	v_and_b32_e32 v134, 0xfc, v143
	ds_write2_b32 v77, v66, v70 offset0:192 offset1:208
	v_add_u32_e32 v70, 0xc400, v131
	s_add_u32 s4, s4, s5
	v_lshlrev_b32_e32 v0, 2, v134
	ds_write2_b32 v70, v67, v71 offset0:196 offset1:212
	v_add_u32_e32 v71, 0xc800, v131
	s_addc_u32 s5, s2, 0
	ds_write2_b32 v71, v68, v72 offset0:200 offset1:216
	v_add_u32_e32 v72, 0xcc00, v131
	v_lshl_add_u64 v[66:67], s[4:5], 0, v[0:1]
	s_mov_b64 s[4:5], 0x2000
	v_add_u32_e32 v130, 0, v0
	ds_write2_b32 v72, v69, v73 offset0:204 offset1:220
	ds_write2_b32 v131, v98, v118 offset0:128 offset1:144
	ds_write2_b32 v114, v99, v119 offset0:132 offset1:148
	ds_write2_b32 v115, v100, v120 offset0:136 offset1:152
	ds_write2_b32 v116, v101, v121 offset0:140 offset1:156
	ds_write2_b32 v117, v102, v122 offset0:192 offset1:208
	ds_write2_b32 v82, v103, v123 offset0:196 offset1:212
	ds_write2_b32 v83, v104, v124 offset0:200 offset1:216
	ds_write2_b32 v84, v105, v125 offset0:204 offset1:220
	ds_write2_b32 v74, v90, v110 offset1:16
	ds_write2_b32 v75, v91, v111 offset0:4 offset1:20
	ds_write2_b32 v76, v92, v112 offset0:8 offset1:24
	v_add_u32_e32 v69, 0x9000, v131
	v_add_u32_e32 v73, 0xd000, v131
	v_lshl_add_u64 v[66:67], v[66:67], 0, s[4:5]
	v_or_b32_e32 v0, s65, v134
	s_mov_b32 s2, 0
	ds_write2_b32 v69, v93, v113 offset0:12 offset1:28
	ds_write2_b32 v70, v86, v106 offset0:64 offset1:80
	ds_write2_b32 v71, v87, v107 offset0:68 offset1:84
	ds_write2_b32 v72, v88, v108 offset0:72 offset1:88
	ds_write2_b32 v73, v89, v109 offset0:76 offset1:92
	s_waitcnt lgkmcnt(0)
	s_barrier
	v_lshrrev_b32_e32 v142, 6, v140
	v_lshlrev_b32_e32 v68, 2, v0
	v_lshl_or_b32 v141, v142, 12, v68
	v_mad_u32_u24 v142, v142, s9, v130
	v_add_u32_e32 v143, 0x10400, v142
	global_load_dwordx4 v[240:243], v[66:67], off
	s_add_u32 s18, s48, 0x0
	s_addc_u32 s19, s49, 0
	global_load_dwordx4 v[144:147], v141, s[18:19] nt
	s_add_u32 s18, s48, 0x8000
	s_addc_u32 s19, s49, 0
	global_load_dwordx4 v[148:151], v141, s[18:19] nt
	s_add_u32 s18, s48, 0x10000
	s_addc_u32 s19, s49, 0
	global_load_dwordx4 v[152:155], v141, s[18:19] nt
	s_add_u32 s18, s48, 0x18000
	s_addc_u32 s19, s49, 0
	global_load_dwordx4 v[156:159], v141, s[18:19] nt
	s_add_u32 s18, s48, 0x20000
	s_addc_u32 s19, s49, 0
	global_load_dwordx4 v[160:163], v141, s[18:19] nt
	s_add_u32 s18, s48, 0x28000
	s_addc_u32 s19, s49, 0
	global_load_dwordx4 v[164:167], v141, s[18:19] nt
	s_add_u32 s18, s48, 0x30000
	s_addc_u32 s19, s49, 0
	global_load_dwordx4 v[168:171], v141, s[18:19] nt
	s_add_u32 s18, s48, 0x38000
	s_addc_u32 s19, s49, 0
	global_load_dwordx4 v[172:175], v141, s[18:19] nt
	s_add_u32 s18, s48, 0x40000
	s_addc_u32 s19, s49, 0
	global_load_dwordx4 v[176:179], v141, s[18:19] nt
	s_add_u32 s18, s48, 0x48000
	s_addc_u32 s19, s49, 0
	global_load_dwordx4 v[180:183], v141, s[18:19] nt
	s_add_u32 s18, s48, 0x50000
	s_addc_u32 s19, s49, 0
	global_load_dwordx4 v[216:219], v141, s[18:19] nt
	s_add_u32 s18, s48, 0x58000
	s_addc_u32 s19, s49, 0
	global_load_dwordx4 v[220:223], v141, s[18:19] nt
	s_add_u32 s18, s48, 0x60000
	s_addc_u32 s19, s49, 0
	global_load_dwordx4 v[224:227], v141, s[18:19] nt
	s_add_u32 s18, s48, 0x68000
	s_addc_u32 s19, s49, 0
	global_load_dwordx4 v[228:231], v141, s[18:19] nt
	s_add_u32 s18, s48, 0x70000
	s_addc_u32 s19, s49, 0
	global_load_dwordx4 v[232:235], v141, s[18:19] nt
	s_add_u32 s18, s48, 0x78000
	s_addc_u32 s19, s49, 0
	global_load_dwordx4 v[236:239], v141, s[18:19] nt
	ds_read_b128 v[244:247], v142 offset:0
	ds_read_b128 v[248:251], v142 offset:8320
	ds_read_b128 v[132:135], v142 offset:16640
	s_add_u32 s20, s50, 0x0
	s_addc_u32 s21, s51, 0
	ds_read_b128 v[136:139], v142 offset:24960
	s_waitcnt vmcnt(15) lgkmcnt(3)
	v_pk_fma_f32 v[246:247], v[246:247], v[242:243], v[146:147]
	v_pk_fma_f32 v[244:245], v[244:245], v[240:241], v[144:145]
	global_store_dwordx4 v141, v[244:247], s[20:21] nt
	s_add_u32 s20, s50, 0x8000
	s_addc_u32 s21, s51, 0
	ds_read_b128 v[244:247], v142 offset:33280
	s_waitcnt vmcnt(15) lgkmcnt(3)
; template <class Epi>
; DI void gemm256(const bf16_t* __restrict__ A, int lda, const bf16_t* __restrict__ Bt, int ldb, int K, char* lds, Epi epi) {
;     ...
; #pragma unroll
;   for (int ai = 0; ai < 2; ++ai) {
;     __syncthreads();
; #pragma unroll
;     for (int bj = 0; bj < 2; ++bj)
; #pragma unroll
;       for (int m = 0; m < 4; ++m)
; #pragma unroll
;         for (int n = 0; n < 2; ++n)
; #pragma unroll
;           for (int j = 0; j < 4; ++j) ct[(wr * 64 + m * 16 + fq * 4 + j) * 260 + bj * 128 + wc * 32 + n * 16 + fr] = acc[ai][bj][m][n][j];
;     __syncthreads();
; #pragma unroll 2
;     for (int it = 0; it < 16; ++it) {
;       const int idx = it * NTHR + tid; const int row = idx >> 6, c4 = (idx & 63) * 4;
;       f32x4 v = *(const f32x4*)(ct + row * 260 + c4);
;       epi(ai * 128 + row, c4, v);
;     }
; DI void phase_outproj(KP p, int l, char* lds) {
;     ...
;         const size_t o = (size_t)m * 1024 + n0 + n;
;         f32x4 xv = __builtin_nontemporal_load((const f32x4*)(src + o)), g = *(const f32x4*)(gt + n0 + n);
;         f32x4 r = {xv[0] + g[0] * v[0], xv[1] + g[1] * v[1], xv[2] + g[2] * v[2], xv[3] + g[3] * v[3]};
;         __builtin_nontemporal_store(r, (f32x4*)(dst + o)); });
	v_pk_fma_f32 v[250:251], v[250:251], v[242:243], v[150:151]
	v_pk_fma_f32 v[248:249], v[248:249], v[240:241], v[148:149]
	global_store_dwordx4 v141, v[248:251], s[20:21] nt
	s_add_u32 s20, s50, 0x10000
	s_addc_u32 s21, s51, 0
	ds_read_b128 v[248:251], v142 offset:41600
	s_waitcnt vmcnt(15) lgkmcnt(3)
	v_pk_fma_f32 v[134:135], v[134:135], v[242:243], v[154:155]
	v_pk_fma_f32 v[132:133], v[132:133], v[240:241], v[152:153]
	global_store_dwordx4 v141, v[132:135], s[20:21] nt
	s_add_u32 s20, s50, 0x18000
	s_addc_u32 s21, s51, 0
	ds_read_b128 v[132:135], v142 offset:49920
	s_waitcnt vmcnt(15) lgkmcnt(3)
	v_pk_fma_f32 v[138:139], v[138:139], v[242:243], v[158:159]
	v_pk_fma_f32 v[136:137], v[136:137], v[240:241], v[156:157]
	global_store_dwordx4 v141, v[136:139], s[20:21] nt
	s_add_u32 s20, s50, 0x20000
	s_addc_u32 s21, s51, 0
	ds_read_b128 v[136:139], v142 offset:58240
	s_waitcnt vmcnt(15) lgkmcnt(3)
	v_pk_fma_f32 v[246:247], v[246:247], v[242:243], v[162:163]
	v_pk_fma_f32 v[244:245], v[244:245], v[240:241], v[160:161]
	global_store_dwordx4 v141, v[244:247], s[20:21] nt
	s_add_u32 s20, s50, 0x28000
	s_addc_u32 s21, s51, 0
	ds_read_b128 v[244:247], v143 offset:0
	s_waitcnt vmcnt(15) lgkmcnt(3)
	v_pk_fma_f32 v[250:251], v[250:251], v[242:243], v[166:167]
	v_pk_fma_f32 v[248:249], v[248:249], v[240:241], v[164:165]
	global_store_dwordx4 v141, v[248:251], s[20:21] nt
	s_add_u32 s20, s50, 0x30000
	s_addc_u32 s21, s51, 0
	ds_read_b128 v[248:251], v143 offset:8320
	s_waitcnt vmcnt(15) lgkmcnt(3)
	v_pk_fma_f32 v[134:135], v[134:135], v[242:243], v[170:171]
	v_pk_fma_f32 v[132:133], v[132:133], v[240:241], v[168:169]
	global_store_dwordx4 v141, v[132:135], s[20:21] nt
	s_add_u32 s20, s50, 0x38000
	s_addc_u32 s21, s51, 0
	ds_read_b128 v[132:135], v143 offset:16640
	s_waitcnt vmcnt(15) lgkmcnt(3)
	v_pk_fma_f32 v[138:139], v[138:139], v[242:243], v[174:175]
	v_pk_fma_f32 v[136:137], v[136:137], v[240:241], v[172:173]
	global_store_dwordx4 v141, v[136:139], s[20:21] nt
	s_add_u32 s20, s50, 0x40000
	s_addc_u32 s21, s51, 0
	ds_read_b128 v[136:139], v143 offset:24960
	s_waitcnt vmcnt(15) lgkmcnt(3)
	v_pk_fma_f32 v[246:247], v[246:247], v[242:243], v[178:179]
	v_pk_fma_f32 v[244:245], v[244:245], v[240:241], v[176:177]
	global_store_dwordx4 v141, v[244:247], s[20:21] nt
	s_add_u32 s20, s50, 0x48000
	s_addc_u32 s21, s51, 0
	ds_read_b128 v[244:247], v143 offset:33280
	s_waitcnt vmcnt(15) lgkmcnt(3)
	v_pk_fma_f32 v[250:251], v[250:251], v[242:243], v[182:183]
	v_pk_fma_f32 v[248:249], v[248:249], v[240:241], v[180:181]
	global_store_dwordx4 v141, v[248:251], s[20:21] nt
	s_add_u32 s20, s50, 0x50000
	s_addc_u32 s21, s51, 0
	ds_read_b128 v[248:251], v143 offset:41600
	s_waitcnt vmcnt(15) lgkmcnt(3)
	v_pk_fma_f32 v[134:135], v[134:135], v[242:243], v[218:219]
	v_pk_fma_f32 v[132:133], v[132:133], v[240:241], v[216:217]
	global_store_dwordx4 v141, v[132:135], s[20:21] nt
	s_add_u32 s20, s50, 0x58000
	s_addc_u32 s21, s51, 0
	ds_read_b128 v[132:135], v143 offset:49920
	s_waitcnt vmcnt(15) lgkmcnt(3)
	v_pk_fma_f32 v[138:139], v[138:139], v[242:243], v[222:223]
	v_pk_fma_f32 v[136:137], v[136:137], v[240:241], v[220:221]
	global_store_dwordx4 v141, v[136:139], s[20:21] nt
	s_add_u32 s20, s50, 0x60000
	s_addc_u32 s21, s51, 0
	ds_read_b128 v[136:139], v143 offset:58240
	s_waitcnt vmcnt(15) lgkmcnt(3)
	v_pk_fma_f32 v[246:247], v[246:247], v[242:243], v[226:227]
	v_pk_fma_f32 v[244:245], v[244:245], v[240:241], v[224:225]
	global_store_dwordx4 v141, v[244:247], s[20:21] nt
	s_add_u32 s20, s50, 0x68000
	s_addc_u32 s21, s51, 0
	s_waitcnt vmcnt(15) lgkmcnt(2)
	v_pk_fma_f32 v[250:251], v[250:251], v[242:243], v[230:231]
	v_pk_fma_f32 v[248:249], v[248:249], v[240:241], v[228:229]
	global_store_dwordx4 v141, v[248:251], s[20:21] nt
	s_add_u32 s20, s50, 0x70000
	s_addc_u32 s21, s51, 0
	s_waitcnt vmcnt(15) lgkmcnt(1)
	v_pk_fma_f32 v[134:135], v[134:135], v[242:243], v[234:235]
	v_pk_fma_f32 v[132:133], v[132:133], v[240:241], v[232:233]
	global_store_dwordx4 v141, v[132:135], s[20:21] nt
	s_add_u32 s20, s50, 0x78000
	s_addc_u32 s21, s51, 0
	s_waitcnt vmcnt(15) lgkmcnt(0)
	v_pk_fma_f32 v[138:139], v[138:139], v[242:243], v[238:239]
	v_pk_fma_f32 v[136:137], v[136:137], v[240:241], v[236:237]
	global_store_dwordx4 v141, v[136:139], s[20:21] nt
	s_mov_b32 s2, 0
	s_barrier
	ds_write2_b32 v131, v2, v18 offset1:16
	ds_write2_b32 v114, v3, v19 offset0:4 offset1:20
	ds_write2_b32 v115, v4, v20 offset0:8 offset1:24
	ds_write2_b32 v116, v5, v21 offset0:12 offset1:28
	ds_write2_b32 v117, v6, v22 offset0:64 offset1:80
	ds_write2_b32 v82, v7, v23 offset0:68 offset1:84
	ds_write2_b32 v83, v8, v24 offset0:72 offset1:88
	ds_write2_b32 v84, v9, v25 offset0:76 offset1:92
	ds_write2_b32 v85, v10, v26 offset0:128 offset1:144
	ds_write2_b32 v74, v11, v27 offset0:132 offset1:148
	ds_write2_b32 v75, v12, v28 offset0:136 offset1:152
	ds_write2_b32 v76, v13, v29 offset0:140 offset1:156
	ds_write2_b32 v77, v14, v30 offset0:192 offset1:208
	ds_write2_b32 v70, v15, v31 offset0:196 offset1:212
	ds_write2_b32 v71, v16, v32 offset0:200 offset1:216
	ds_write2_b32 v72, v17, v33 offset0:204 offset1:220
	ds_write2_b32 v131, v34, v50 offset0:128 offset1:144
	ds_write2_b32 v114, v35, v51 offset0:132 offset1:148
	ds_write2_b32 v115, v36, v52 offset0:136 offset1:152
	ds_write2_b32 v116, v37, v53 offset0:140 offset1:156
	ds_write2_b32 v117, v38, v54 offset0:192 offset1:208
	ds_write2_b32 v82, v39, v55 offset0:196 offset1:212
	ds_write2_b32 v83, v40, v56 offset0:200 offset1:216
	ds_write2_b32 v84, v41, v57 offset0:204 offset1:220
	ds_write2_b32 v74, v42, v58 offset1:16
	ds_write2_b32 v75, v43, v59 offset0:4 offset1:20
	ds_write2_b32 v76, v44, v60 offset0:8 offset1:24
	ds_write2_b32 v69, v45, v61 offset0:12 offset1:28
	ds_write2_b32 v70, v46, v62 offset0:64 offset1:80
	ds_write2_b32 v71, v47, v63 offset0:68 offset1:84
	ds_write2_b32 v72, v48, v64 offset0:72 offset1:88
	ds_write2_b32 v73, v49, v65 offset0:76 offset1:92
	s_waitcnt lgkmcnt(0)
	s_barrier
; template <class Epi>
; DI void gemm256(const bf16_t* __restrict__ A, int lda, const bf16_t* __restrict__ Bt, int ldb, int K, char* lds, Epi epi) {
;     ...
; #pragma unroll
;   for (int ai = 0; ai < 2; ++ai) {
;     __syncthreads();
; #pragma unroll
;     for (int bj = 0; bj < 2; ++bj)
; #pragma unroll
;       for (int m = 0; m < 4; ++m)
; #pragma unroll
;         for (int n = 0; n < 2; ++n)
; #pragma unroll
;           for (int j = 0; j < 4; ++j) ct[(wr * 64 + m * 16 + fq * 4 + j) * 260 + bj * 128 + wc * 32 + n * 16 + fr] = acc[ai][bj][m][n][j];
;     __syncthreads();
; #pragma unroll 2
;     for (int it = 0; it < 16; ++it) {
;       const int idx = it * NTHR + tid; const int row = idx >> 6, c4 = (idx & 63) * 4;
;       f32x4 v = *(const f32x4*)(ct + row * 260 + c4);
;       epi(ai * 128 + row, c4, v);
;     }
; DI void phase_outproj(KP p, int l, char* lds) {
;     ...
;   for (int j = lb; j < 64; j += nlb) {
;     {
;       const int mi = j >> 2, nt = j & 3;
;       const int bb = 2 * xcd + (mi >> 3), tt = mi & 7;
;       const int m0 = (bb * 9 + tt) * 256, n0 = nt * 256;
;       const float* src = xl + ((size_t)bb * SEQ + tt * 256) * 1024;
;       float* dst = p->out + ((size_t)bb * SEQ + tt * 256) * 1024;
;       const float* gt = mod + (size_t)bb * 3072 + 2048;
;       gemm256(Y + (size_t)m0 * 1024, 1024, wo + (size_t)n0 * 1024, 1024, 1024, lds, [&](int m, int n, f32x4 v) {
;         const size_t o = (size_t)m * 1024 + n0 + n;
;         f32x4 xv = __builtin_nontemporal_load((const f32x4*)(src + o)), g = *(const f32x4*)(gt + n0 + n);
;         f32x4 r = {xv[0] + g[0] * v[0], xv[1] + g[1] * v[1], xv[2] + g[2] * v[2], xv[3] + g[3] * v[3]};
;         __builtin_nontemporal_store(r, (f32x4*)(dst + o)); });
;     }
;   }
	s_add_u32 s18, s48, 0x80000
	s_addc_u32 s19, s49, 0
	global_load_dwordx4 v[144:147], v141, s[18:19] nt
	s_add_u32 s18, s48, 0x88000
	s_addc_u32 s19, s49, 0
	global_load_dwordx4 v[148:151], v141, s[18:19] nt
	s_add_u32 s18, s48, 0x90000
	s_addc_u32 s19, s49, 0
	global_load_dwordx4 v[152:155], v141, s[18:19] nt
	s_add_u32 s18, s48, 0x98000
	s_addc_u32 s19, s49, 0
	global_load_dwordx4 v[156:159], v141, s[18:19] nt
	s_add_u32 s18, s48, 0xa0000
	s_addc_u32 s19, s49, 0
	global_load_dwordx4 v[160:163], v141, s[18:19] nt
	s_add_u32 s18, s48, 0xa8000
	s_addc_u32 s19, s49, 0
	global_load_dwordx4 v[164:167], v141, s[18:19] nt
	s_add_u32 s18, s48, 0xb0000
	s_addc_u32 s19, s49, 0
	global_load_dwordx4 v[168:171], v141, s[18:19] nt
	s_add_u32 s18, s48, 0xb8000
	s_addc_u32 s19, s49, 0
	global_load_dwordx4 v[172:175], v141, s[18:19] nt
	s_add_u32 s18, s48, 0xc0000
	s_addc_u32 s19, s49, 0
	global_load_dwordx4 v[176:179], v141, s[18:19] nt
	s_add_u32 s18, s48, 0xc8000
	s_addc_u32 s19, s49, 0
	global_load_dwordx4 v[180:183], v141, s[18:19] nt
	s_add_u32 s18, s48, 0xd0000
	s_addc_u32 s19, s49, 0
	global_load_dwordx4 v[216:219], v141, s[18:19] nt
	s_add_u32 s18, s48, 0xd8000
	s_addc_u32 s19, s49, 0
	global_load_dwordx4 v[220:223], v141, s[18:19] nt
	s_add_u32 s18, s48, 0xe0000
	s_addc_u32 s19, s49, 0
	global_load_dwordx4 v[224:227], v141, s[18:19] nt
	s_add_u32 s18, s48, 0xe8000
	s_addc_u32 s19, s49, 0
	global_load_dwordx4 v[228:231], v141, s[18:19] nt
	s_add_u32 s18, s48, 0xf0000
	s_addc_u32 s19, s49, 0
	global_load_dwordx4 v[232:235], v141, s[18:19] nt
	s_add_u32 s18, s48, 0xf8000
	s_addc_u32 s19, s49, 0
	global_load_dwordx4 v[236:239], v141, s[18:19] nt
	ds_read_b128 v[244:247], v142 offset:0
	ds_read_b128 v[248:251], v142 offset:8320
	ds_read_b128 v[132:135], v142 offset:16640
	s_add_u32 s20, s50, 0x80000
	s_addc_u32 s21, s51, 0
	ds_read_b128 v[136:139], v142 offset:24960
	s_waitcnt vmcnt(15) lgkmcnt(3)
	v_pk_fma_f32 v[246:247], v[246:247], v[242:243], v[146:147]
	v_pk_fma_f32 v[244:245], v[244:245], v[240:241], v[144:145]
	global_store_dwordx4 v141, v[244:247], s[20:21] nt
	s_add_u32 s20, s50, 0x88000
	s_addc_u32 s21, s51, 0
	ds_read_b128 v[244:247], v142 offset:33280
	s_waitcnt vmcnt(15) lgkmcnt(3)
	v_pk_fma_f32 v[250:251], v[250:251], v[242:243], v[150:151]
	v_pk_fma_f32 v[248:249], v[248:249], v[240:241], v[148:149]
	global_store_dwordx4 v141, v[248:251], s[20:21] nt
	s_add_u32 s20, s50, 0x90000
	s_addc_u32 s21, s51, 0
	ds_read_b128 v[248:251], v142 offset:41600
	s_waitcnt vmcnt(15) lgkmcnt(3)
	v_pk_fma_f32 v[134:135], v[134:135], v[242:243], v[154:155]
	v_pk_fma_f32 v[132:133], v[132:133], v[240:241], v[152:153]
	global_store_dwordx4 v141, v[132:135], s[20:21] nt
	s_add_u32 s20, s50, 0x98000
	s_addc_u32 s21, s51, 0
	ds_read_b128 v[132:135], v142 offset:49920
	s_waitcnt vmcnt(15) lgkmcnt(3)
	v_pk_fma_f32 v[138:139], v[138:139], v[242:243], v[158:159]
	v_pk_fma_f32 v[136:137], v[136:137], v[240:241], v[156:157]
	global_store_dwordx4 v141, v[136:139], s[20:21] nt
	s_add_u32 s20, s50, 0xa0000
	s_addc_u32 s21, s51, 0
	ds_read_b128 v[136:139], v142 offset:58240
	s_waitcnt vmcnt(15) lgkmcnt(3)
	v_pk_fma_f32 v[246:247], v[246:247], v[242:243], v[162:163]
	v_pk_fma_f32 v[244:245], v[244:245], v[240:241], v[160:161]
	global_store_dwordx4 v141, v[244:247], s[20:21] nt
	s_add_u32 s20, s50, 0xa8000
	s_addc_u32 s21, s51, 0
	ds_read_b128 v[244:247], v143 offset:0
	s_waitcnt vmcnt(15) lgkmcnt(3)
	v_pk_fma_f32 v[250:251], v[250:251], v[242:243], v[166:167]
	v_pk_fma_f32 v[248:249], v[248:249], v[240:241], v[164:165]
	global_store_dwordx4 v141, v[248:251], s[20:21] nt
	s_add_u32 s20, s50, 0xb0000
	s_addc_u32 s21, s51, 0
	ds_read_b128 v[248:251], v143 offset:8320
	s_waitcnt vmcnt(15) lgkmcnt(3)
	v_pk_fma_f32 v[134:135], v[134:135], v[242:243], v[170:171]
	v_pk_fma_f32 v[132:133], v[132:133], v[240:241], v[168:169]
	global_store_dwordx4 v141, v[132:135], s[20:21] nt
	s_add_u32 s20, s50, 0xb8000
	s_addc_u32 s21, s51, 0
	ds_read_b128 v[132:135], v143 offset:16640
	s_waitcnt vmcnt(15) lgkmcnt(3)
	v_pk_fma_f32 v[138:139], v[138:139], v[242:243], v[174:175]
	v_pk_fma_f32 v[136:137], v[136:137], v[240:241], v[172:173]
	global_store_dwordx4 v141, v[136:139], s[20:21] nt
	s_add_u32 s20, s50, 0xc0000
	s_addc_u32 s21, s51, 0
	ds_read_b128 v[136:139], v143 offset:24960
	s_waitcnt vmcnt(15) lgkmcnt(3)
	v_pk_fma_f32 v[246:247], v[246:247], v[242:243], v[178:179]
	v_pk_fma_f32 v[244:245], v[244:245], v[240:241], v[176:177]
	global_store_dwordx4 v141, v[244:247], s[20:21] nt
	s_add_u32 s20, s50, 0xc8000
	s_addc_u32 s21, s51, 0
	ds_read_b128 v[244:247], v143 offset:33280
	s_waitcnt vmcnt(15) lgkmcnt(3)
	v_pk_fma_f32 v[250:251], v[250:251], v[242:243], v[182:183]
	v_pk_fma_f32 v[248:249], v[248:249], v[240:241], v[180:181]
	global_store_dwordx4 v141, v[248:251], s[20:21] nt
	s_add_u32 s20, s50, 0xd0000
	s_addc_u32 s21, s51, 0
	ds_read_b128 v[248:251], v143 offset:41600
	s_waitcnt vmcnt(15) lgkmcnt(3)
	v_pk_fma_f32 v[134:135], v[134:135], v[242:243], v[218:219]
	v_pk_fma_f32 v[132:133], v[132:133], v[240:241], v[216:217]
	global_store_dwordx4 v141, v[132:135], s[20:21] nt
	s_add_u32 s20, s50, 0xd8000
	s_addc_u32 s21, s51, 0
	ds_read_b128 v[132:135], v143 offset:49920
	s_waitcnt vmcnt(15) lgkmcnt(3)
	v_pk_fma_f32 v[138:139], v[138:139], v[242:243], v[222:223]
	v_pk_fma_f32 v[136:137], v[136:137], v[240:241], v[220:221]
	global_store_dwordx4 v141, v[136:139], s[20:21] nt
	s_add_u32 s20, s50, 0xe0000
	s_addc_u32 s21, s51, 0
	ds_read_b128 v[136:139], v143 offset:58240
	s_waitcnt vmcnt(15) lgkmcnt(3)
	v_pk_fma_f32 v[246:247], v[246:247], v[242:243], v[226:227]
	v_pk_fma_f32 v[244:245], v[244:245], v[240:241], v[224:225]
	global_store_dwordx4 v141, v[244:247], s[20:21] nt
	s_add_u32 s20, s50, 0xe8000
	s_addc_u32 s21, s51, 0
	s_waitcnt vmcnt(15) lgkmcnt(2)
	v_pk_fma_f32 v[250:251], v[250:251], v[242:243], v[230:231]
	v_pk_fma_f32 v[248:249], v[248:249], v[240:241], v[228:229]
	global_store_dwordx4 v141, v[248:251], s[20:21] nt
	s_add_u32 s20, s50, 0xf0000
	s_addc_u32 s21, s51, 0
	s_waitcnt vmcnt(15) lgkmcnt(1)
	v_pk_fma_f32 v[134:135], v[134:135], v[242:243], v[234:235]
	v_pk_fma_f32 v[132:133], v[132:133], v[240:241], v[232:233]
	global_store_dwordx4 v141, v[132:135], s[20:21] nt
	s_add_u32 s20, s50, 0xf8000
	s_addc_u32 s21, s51, 0
	s_waitcnt vmcnt(15) lgkmcnt(0)
	v_pk_fma_f32 v[138:139], v[138:139], v[242:243], v[238:239]
	v_pk_fma_f32 v[136:137], v[136:137], v[240:241], v[236:237]
	global_store_dwordx4 v141, v[136:139], s[20:21] nt
	v_readlane_b32 s2, v254, 45
	s_add_i32 s64, s64, s69
	s_add_i32 s57, s57, s2
	s_cmp_gt_u32 s64, 63
	s_barrier
	s_cbranch_scc0 .LBB0_343
